# log2(e) folded into q_a's single bf16 rounding (P1 epilogue post-scale, prompt rows) and the f32 bias table; prompt attention softmax = exp2 of the MFMA result, fixed shift dropped when mL<=60 (shifte
# speedup vs baseline: 1.0171x; 1.0171x over previous
.LBB0_164:
	v_readlane_b32 s96, v242, 26
	s_lshl_b32 s17, s18, 8
	s_mov_b64 s[34:35], 0x400
	s_mov_b64 s[46:47], 0
	s_mov_b32 s24, 0x3e38aa3b
	s_cmp_gt_i32 s16, 63
	s_cselect_b32 s24, 0x3e000000, s24
	s_mov_b64 s[44:45], -1
	s_mov_b64 s[50:51], 0
	s_mov_b64 s[92:93], 0
	s_mov_b64 s[56:57], 0
	v_readlane_b32 s97, v242, 27
	s_mov_b64 s[94:95], -1
	s_mov_b64 s[20:21], -1

.LBB0_447:
	s_or_b64 exec, exec, s[38:39]
	v_cmp_lt_i32_e32 vcc, s46, v2
	s_nop 1
	v_cndmask_b32_e64 v4, 0, 16, vcc
	v_add_u32_e32 v0, v0, v4
	v_lshl_or_b32 v0, v0, 4, s62
	v_lshl_add_u64 v[4:5], v[0:1], 2, s[66:67]
	global_load_dword v0, v[4:5], off
	s_nop 0
	global_load_dword v4, v1, s[18:19] offset:960
	v_lshl_add_u32 v5, v2, 2, 0
	s_waitcnt vmcnt(0)
	v_sub_f32_e32 v0, v0, v4
	v_mul_f32_e32 v0, 0x3fb8aa3b, v0
	v_add_u32_e32 v4, 0x19800, v5
	ds_write_b32 v4, v0
.LBB0_448:
	s_or_b64 exec, exec, s[34:35]
	s_xor_b64 s[34:35], s[20:21], -1
	s_and_b64 s[20:21], s[20:21], exec
	v_add_u32_e32 v6, 0x200, v2
	v_add_u32_e32 v14, 0x400, v2
	v_add_u32_e32 v16, 0x600, v2
	s_cselect_b32 s20, s63, s64
	v_ashrrev_i32_e32 v23, 4, v2
	v_ashrrev_i32_e32 v28, 4, v6
	v_ashrrev_i32_e32 v30, 4, v14
	v_ashrrev_i32_e32 v32, 4, v16
	s_lshl_b32 s38, s20, 7
	v_min_i32_e32 v4, 0x7f, v23
	v_min_i32_e32 v6, 0x7f, v28
	v_min_i32_e32 v14, 0x7f, v30
	v_min_i32_e32 v16, 0x7f, v32
	v_lshlrev_b32_e32 v0, 4, v2
	v_add_u32_e32 v4, s38, v4
	v_add_u32_e32 v6, s38, v6
	v_add_u32_e32 v14, s38, v14
	v_add_u32_e32 v16, s38, v16
	v_and_b32_e32 v0, 0xf0, v0
	v_ashrrev_i32_e32 v5, 31, v4
	v_ashrrev_i32_e32 v7, 31, v6
	v_ashrrev_i32_e32 v15, 31, v14
	v_ashrrev_i32_e32 v17, 31, v16
	v_lshl_add_u64 v[12:13], s[10:11], 0, v[0:1]
	v_lshlrev_b64 v[4:5], 11, v[4:5]
	v_lshlrev_b64 v[6:7], 11, v[6:7]
	v_lshlrev_b64 v[14:15], 11, v[14:15]
	v_lshlrev_b64 v[16:17], 11, v[16:17]
	v_lshl_add_u64 v[4:5], v[12:13], 0, v[4:5]
	v_lshl_add_u64 v[8:9], v[12:13], 0, v[6:7]
	v_lshl_add_u64 v[14:15], v[12:13], 0, v[14:15]
	v_lshl_add_u64 v[16:17], v[12:13], 0, v[16:17]
	global_load_dwordx4 v[4:7], v[4:5], off
	s_nop 0
	global_load_dwordx4 v[8:11], v[8:9], off
	s_nop 0
	global_load_dwordx4 v[12:15], v[14:15], off
	s_nop 0
	global_load_dwordx4 v[16:19], v[16:17], off
	v_ashrrev_i32_e32 v20, 3, v2
	v_ashrrev_i32_e32 v21, 31, v20
	v_lshlrev_b32_e32 v26, 5, v2
	s_add_i32 s20, 0, 0x11000
	v_lshlrev_b64 v[24:25], 11, v[20:21]
	v_add_u32_e32 v22, s20, v0
	v_and_b32_e32 v0, 0xe0, v26
	v_lshl_add_u64 v[24:25], s[12:13], 0, v[24:25]
	v_mad_u64_u32 v[26:27], s[20:21], v23, s51, v[22:23]
	v_lshl_add_u64 v[24:25], v[24:25], 0, v[0:1]
	v_mad_u64_u32 v[28:29], s[20:21], v28, s51, v[22:23]
	v_mad_u64_u32 v[30:31], s[20:21], v30, s51, v[22:23]
	v_mad_u64_u32 v[22:23], s[20:21], v32, s51, v[22:23]
	v_lshlrev_b32_e32 v3, 4, v3
	v_and_b32_e32 v165, 31, v2
	s_lshl_b32 s39, s65, 5
	s_ashr_i32 s40, s65, 2
	s_and_b32 s20, s39, 0x60
	v_or_b32_e32 v174, s20, v165
	s_lshl_b32 s41, s40, 7
	s_or_b32 s21, s38, 0x7f
	v_mov_b32_e32 v79, 0
	s_cmpk_lt_i32 s21, 0xffc1
	v_mov_b32_e32 v78, 0
	v_mov_b32_e32 v77, 0
	v_mov_b32_e32 v76, 0
	v_mov_b32_e32 v75, 0
	v_mov_b32_e32 v74, 0
	v_mov_b32_e32 v73, 0
	v_mov_b32_e32 v72, 0
	v_mov_b32_e32 v71, 0
	v_mov_b32_e32 v70, 0
	v_mov_b32_e32 v69, 0
	v_mov_b32_e32 v68, 0
	v_mov_b32_e32 v67, 0
	v_mov_b32_e32 v66, 0
	v_mov_b32_e32 v65, 0
	v_mov_b32_e32 v64, v79
	v_mov_b32_e32 v63, 0
	v_mov_b32_e32 v62, 0
	v_mov_b32_e32 v61, 0
	v_mov_b32_e32 v60, 0
	v_mov_b32_e32 v59, 0
	v_mov_b32_e32 v58, 0
	v_mov_b32_e32 v57, 0
	v_mov_b32_e32 v56, 0
	v_mov_b32_e32 v55, 0
	v_mov_b32_e32 v54, 0
	s_waitcnt vmcnt(3)
	ds_write_b128 v26, v[4:7]
	s_waitcnt vmcnt(2)
	ds_write_b128 v28, v[8:11]
	s_waitcnt vmcnt(1)
	ds_write_b128 v30, v[12:15]
	s_waitcnt vmcnt(0)
	ds_write_b128 v22, v[16:19]
	global_load_dwordx4 v[4:7], v[24:25], off
	global_load_dwordx4 v[8:11], v[24:25], off offset:16
	v_bfe_u32 v12, v2, 2, 4
	v_ashrrev_i32_e32 v14, 5, v2
	v_and_or_b32 v3, v3, 16, v12
	v_bfi_b32 v16, -4, v14, v2
	v_mov_b32_e32 v13, v1
	v_mul_lo_u32 v15, v20, s51
	v_lshlrev_b32_e32 v12, 12, v3
	v_lshlrev_b32_e32 v14, 3, v16
	v_add_u32_e32 v17, 0, v15
	v_lshl_add_u64 v[12:13], s[14:15], 0, v[12:13]
	v_ashrrev_i32_e32 v15, 31, v14
	v_add_u32_e32 v176, v17, v0
	v_lshl_add_u64 v[12:13], v[14:15], 1, v[12:13]
	v_bfe_u32 v0, v2, 5, 1
	v_mul_lo_u32 v2, v16, s56
	v_lshlrev_b32_e32 v3, 2, v3
	v_add_u32_e32 v2, 0, v2
	v_add_u32_e32 v177, v2, v3
	v_add_u32_e32 v178, 0x8800, v177
	v_lshl_add_u64 v[166:167], v[24:25], 0, s[4:5]
	v_lshlrev_b32_e32 v173, 4, v0
	v_lshlrev_b32_e32 v164, 3, v0
	v_mov_b32_e32 v53, 0
	v_mov_b32_e32 v52, 0
	v_mov_b32_e32 v51, 0
	v_mov_b32_e32 v50, 0
	v_mov_b32_e32 v49, 0
	v_mov_b32_e32 v48, v79
	v_mov_b32_e32 v47, 0
	v_mov_b32_e32 v46, 0
	v_mov_b32_e32 v45, 0
	v_mov_b32_e32 v44, 0
	v_mov_b32_e32 v43, 0
	v_mov_b32_e32 v42, 0
	v_mov_b32_e32 v41, 0
	v_mov_b32_e32 v40, 0
	v_mov_b32_e32 v39, 0
	v_mov_b32_e32 v38, 0
	v_mov_b32_e32 v37, 0
	v_mov_b32_e32 v36, 0
	v_mov_b32_e32 v35, 0
	v_mov_b32_e32 v34, 0
	v_mov_b32_e32 v33, 0
	v_mov_b32_e32 v32, v79
	v_mov_b32_e32 v31, 0
	v_mov_b32_e32 v30, 0
	v_mov_b32_e32 v29, 0
	v_mov_b32_e32 v28, 0
	v_mov_b32_e32 v27, 0
	v_mov_b32_e32 v26, 0
	v_mov_b32_e32 v25, 0
	s_waitcnt vmcnt(1)
	ds_write_b128 v176, v[4:7]
	s_waitcnt vmcnt(0)
	ds_write_b128 v176, v[8:11] offset:16
	global_load_dwordx4 v[4:7], v[12:13], off
	global_load_dwordx4 v[8:11], v[12:13], off offset:2048
	v_lshl_add_u64 v[168:169], v[12:13], 0, s[4:5]
	v_mov_b32_e32 v24, 0
	v_mov_b32_e32 v23, 0
	v_mov_b32_e32 v22, 0
	v_mov_b32_e32 v21, 0
	v_mov_b32_e32 v20, 0
	v_mov_b32_e32 v19, 0
	v_mov_b32_e32 v18, 0
	v_mov_b32_e32 v17, 0
	v_mov_b32_e32 v16, v79
	v_mov_b32_e32 v175, 0
	s_waitcnt vmcnt(1)
	v_and_b32_e32 v2, 0xffff, v4
	v_lshrrev_b32_e32 v3, 16, v4
	v_and_b32_e32 v4, 0xffff, v5
	v_lshrrev_b32_e32 v5, 16, v5
	v_and_b32_e32 v12, 0xffff, v6
	v_lshrrev_b32_e32 v6, 16, v6
	v_and_b32_e32 v13, 0xffff, v7
	v_lshrrev_b32_e32 v7, 16, v7
	s_waitcnt vmcnt(0)
	v_lshl_or_b32 v2, v8, 16, v2
	v_and_or_b32 v3, v8, s57, v3
	v_lshl_or_b32 v4, v9, 16, v4
	v_and_or_b32 v5, v9, s57, v5
	v_lshl_or_b32 v8, v10, 16, v12
	v_and_or_b32 v6, v10, s57, v6
	v_lshl_or_b32 v9, v11, 16, v13
	v_and_or_b32 v7, v11, s57, v7
	ds_write2_b32 v178, v2, v3 offset1:34
	ds_write2_b32 v178, v4, v5 offset0:68 offset1:102
	ds_write2_b32 v178, v8, v6 offset0:136 offset1:170
	ds_write2_b32 v178, v9, v7 offset0:204 offset1:238
	global_load_dwordx4 v[120:123], v[166:167], off offset:16
	global_load_dwordx4 v[124:127], v[166:167], off
	global_load_dwordx4 v[116:119], v[168:169], off
	global_load_dwordx4 v[112:115], v[168:169], off offset:2048
	v_mul_u32_u24_e32 v2, 0x110, v174
	v_or_b32_e32 v3, s41, v173
	v_add3_u32 v179, v3, v2, s50
	v_mul_u32_u24_e32 v2, 0x88, v165
	v_mul_u32_u24_e32 v3, 0x110, v165
	v_add3_u32 v2, v2, v164, s58
	v_add3_u32 v180, v173, v3, s41
	s_waitcnt lgkmcnt(0)
	s_barrier
	s_cbranch_scc1 .LBB0_465
	s_ashr_i32 s41, s21, 31
	v_lshlrev_b32_e32 v0, 2, v0
	s_lshr_b32 s41, s41, 26
	v_sub_u32_e32 v0, v0, v165
	s_add_i32 s21, s21, s41
	v_subrev_u32_e32 v0, s20, v0
	v_mov_b32_e32 v14, v1
	v_mov_b32_e32 v15, v1
	s_ashr_i32 s21, s21, 6
	s_or_b32 s42, s20, s38
	v_add_u32_e32 v181, 0, v2
	v_subrev_u32_e32 v182, s38, v0
	v_mov_b32_e32 v0, v1
	v_mov_b32_e32 v2, v1
	v_mov_b32_e32 v3, v1
	v_mov_b32_e32 v4, v1
	v_mov_b32_e32 v5, v1
	v_mov_b32_e32 v6, v1
	v_mov_b32_e32 v7, v1
	v_mov_b32_e32 v8, v1
	v_mov_b32_e32 v9, v1
	v_mov_b32_e32 v10, v1
	v_mov_b32_e32 v11, v1
	v_mov_b32_e32 v12, v1
	v_mov_b32_e32 v13, v1
	v_mov_b64_e32 v[30:31], v[14:15]
	v_mov_b64_e32 v[46:47], v[14:15]
	v_mov_b64_e32 v[62:63], v[14:15]
	v_mov_b64_e32 v[78:79], v[14:15]
	s_min_i32 s41, s21, 0xff
	s_ashr_i32 s43, s42, 6
	s_mov_b32 s44, 0
	v_mov_b32_e32 v175, 0
	s_movk_i32 s45, 0xda
	v_mov_b64_e32 v[28:29], v[12:13]
	v_mov_b64_e32 v[26:27], v[10:11]
	v_mov_b64_e32 v[24:25], v[8:9]
	v_mov_b64_e32 v[22:23], v[6:7]
	v_mov_b64_e32 v[20:21], v[4:5]
	v_mov_b64_e32 v[18:19], v[2:3]
	v_mov_b64_e32 v[16:17], v[0:1]
	v_mov_b64_e32 v[44:45], v[12:13]
	v_mov_b64_e32 v[42:43], v[10:11]
	v_mov_b64_e32 v[40:41], v[8:9]
	v_mov_b64_e32 v[38:39], v[6:7]
	v_mov_b64_e32 v[36:37], v[4:5]
	v_mov_b64_e32 v[34:35], v[2:3]
	v_mov_b64_e32 v[32:33], v[0:1]
	v_mov_b64_e32 v[60:61], v[12:13]
	v_mov_b64_e32 v[58:59], v[10:11]
	v_mov_b64_e32 v[56:57], v[8:9]
	v_mov_b64_e32 v[54:55], v[6:7]
	v_mov_b64_e32 v[52:53], v[4:5]
	v_mov_b64_e32 v[50:51], v[2:3]
	v_mov_b64_e32 v[48:49], v[0:1]
	v_mov_b64_e32 v[76:77], v[12:13]
	v_mov_b64_e32 v[74:75], v[10:11]
	v_mov_b64_e32 v[72:73], v[8:9]
	v_mov_b64_e32 v[70:71], v[6:7]
	v_mov_b64_e32 v[68:69], v[4:5]
	v_mov_b64_e32 v[66:67], v[2:3]
	v_mov_b64_e32 v[64:65], v[0:1]
	v_cmp_gt_f32_e32 vcc, 0xc2700000, v171
	s_cbranch_vccnz .LBB0_451
	s_branch .Lqf_451

.LBB0_454:
	s_nop 8
	v_add_f32_e32 v0, v80, v171
	v_exp_f32_e32 v132, v0
	v_add_f32_e32 v0, v96, v171
	v_exp_f32_e32 v136, v0
	v_add_f32_e32 v0, v81, v171
	v_add_f32_e32 v80, v97, v171
	v_exp_f32_e32 v0, v0
	v_exp_f32_e32 v80, v80
	v_add_f32_e32 v81, v136, v132
	v_cvt_pk_bf16_f32 v132, v132, v0
	v_pk_add_f32 v[96:97], v[80:81], v[0:1]
	v_add_f32_e32 v81, v82, v171
	v_add_f32_e32 v82, v98, v171
	v_pk_add_f32 v[96:97], v[96:97], v[96:97] op_sel_hi:[0,1]
	v_exp_f32_e32 v137, v82
	v_add_f32_e32 v82, v83, v171
	v_exp_f32_e32 v81, v81
	v_exp_f32_e32 v96, v82
	v_add_f32_e32 v82, v99, v171
	v_exp_f32_e32 v82, v82
	v_add_f32_e32 v83, v137, v81
	v_cvt_pk_bf16_f32 v133, v81, v96
	v_cvt_pk_bf16_f32 v136, v136, v80
	v_pk_add_f32 v[98:99], v[82:83], v[96:97]
	v_add_f32_e32 v83, v84, v171
	v_add_f32_e32 v84, v100, v171
	v_pk_add_f32 v[98:99], v[98:99], v[98:99] op_sel_hi:[0,1]
	v_exp_f32_e32 v97, v84
	v_add_f32_e32 v84, v85, v171
	v_exp_f32_e32 v83, v83
	v_exp_f32_e32 v98, v84
	v_add_f32_e32 v84, v101, v171
	v_exp_f32_e32 v84, v84
	v_add_f32_e32 v85, v97, v83
	v_cvt_pk_bf16_f32 v134, v83, v98
	v_cvt_pk_bf16_f32 v137, v137, v82
	v_pk_add_f32 v[100:101], v[84:85], v[98:99]
	v_add_f32_e32 v85, v86, v171
	v_add_f32_e32 v86, v102, v171
	v_pk_add_f32 v[100:101], v[100:101], v[100:101] op_sel_hi:[0,1]
	v_exp_f32_e32 v99, v86
	v_add_f32_e32 v86, v87, v171
	v_exp_f32_e32 v85, v85
	v_exp_f32_e32 v100, v86
	v_add_f32_e32 v86, v103, v171
	v_exp_f32_e32 v86, v86
	v_add_f32_e32 v87, v99, v85
	v_cvt_pk_bf16_f32 v135, v85, v100
	v_cvt_pk_bf16_f32 v138, v97, v84
	v_pk_add_f32 v[102:103], v[86:87], v[100:101]
	v_add_f32_e32 v87, v88, v171
	v_add_f32_e32 v88, v104, v171
	v_pk_add_f32 v[102:103], v[102:103], v[102:103] op_sel_hi:[0,1]
	v_exp_f32_e32 v101, v88
	v_add_f32_e32 v88, v89, v171
	v_exp_f32_e32 v87, v87
	v_exp_f32_e32 v102, v88
	v_add_f32_e32 v88, v105, v171
	v_exp_f32_e32 v88, v88
	v_add_f32_e32 v89, v101, v87
	v_cvt_pk_bf16_f32 v139, v99, v86
	v_cvt_pk_bf16_f32 v140, v87, v102
	v_pk_add_f32 v[104:105], v[88:89], v[102:103]
	v_add_f32_e32 v89, v90, v171
	v_add_f32_e32 v90, v106, v171
	v_pk_add_f32 v[104:105], v[104:105], v[104:105] op_sel_hi:[0,1]
	v_exp_f32_e32 v103, v90
	v_add_f32_e32 v90, v91, v171
	v_exp_f32_e32 v89, v89
	v_exp_f32_e32 v104, v90
	v_add_f32_e32 v90, v107, v171
	v_exp_f32_e32 v90, v90
	v_add_f32_e32 v91, v103, v89
	v_cvt_pk_bf16_f32 v141, v89, v104
	v_cvt_pk_bf16_f32 v144, v101, v88
	v_pk_add_f32 v[106:107], v[90:91], v[104:105]
	v_add_f32_e32 v91, v92, v171
	v_add_f32_e32 v92, v108, v171
	v_pk_add_f32 v[106:107], v[106:107], v[106:107] op_sel_hi:[0,1]
	v_exp_f32_e32 v105, v92
	v_add_f32_e32 v92, v93, v171
	v_exp_f32_e32 v91, v91
	v_exp_f32_e32 v106, v92
	v_add_f32_e32 v92, v109, v171
	v_exp_f32_e32 v92, v92
	v_add_f32_e32 v93, v105, v91
	v_cvt_pk_bf16_f32 v142, v91, v106
	v_cvt_pk_bf16_f32 v145, v103, v90
	v_pk_add_f32 v[108:109], v[92:93], v[106:107]
	v_add_f32_e32 v93, v94, v171
	v_add_f32_e32 v94, v110, v171
	v_pk_add_f32 v[108:109], v[108:109], v[108:109] op_sel_hi:[0,1]
	v_exp_f32_e32 v107, v94
	v_add_f32_e32 v94, v95, v171
	v_exp_f32_e32 v93, v93
	v_exp_f32_e32 v108, v94
	v_add_f32_e32 v94, v111, v171
	v_exp_f32_e32 v94, v94
	v_add_f32_e32 v95, v107, v93
	v_cvt_pk_bf16_f32 v143, v93, v108
	v_cvt_pk_bf16_f32 v146, v105, v92
	v_pk_add_f32 v[110:111], v[94:95], v[108:109]
	v_cvt_pk_bf16_f32 v147, v107, v94
	v_add_f32_e32 v95, v110, v111
	v_add_f32_e32 v175, v175, v95

.LBB0_461:
	s_nop 8
	v_add_f32_e32 v0, v80, v171
	v_exp_f32_e32 v148, v0
	v_add_f32_e32 v0, v96, v171
	v_exp_f32_e32 v152, v0
	v_add_f32_e32 v0, v81, v171
	v_add_f32_e32 v14, v97, v171
	v_exp_f32_e32 v0, v0
	v_exp_f32_e32 v14, v14
	v_add_f32_e32 v15, v152, v148
	v_cvt_pk_bf16_f32 v148, v148, v0
	v_pk_add_f32 v[80:81], v[14:15], v[0:1]
	v_add_f32_e32 v15, v82, v171
	v_pk_add_f32 v[80:81], v[80:81], v[80:81] op_sel_hi:[0,1]
	v_add_f32_e32 v80, v98, v171
	v_exp_f32_e32 v15, v15
	v_exp_f32_e32 v153, v80
	v_add_f32_e32 v80, v83, v171
	v_add_f32_e32 v82, v99, v171
	v_exp_f32_e32 v80, v80
	v_exp_f32_e32 v82, v82
	v_add_f32_e32 v83, v153, v15
	v_cvt_pk_bf16_f32 v152, v152, v14
	v_cvt_pk_bf16_f32 v149, v15, v80
	v_pk_add_f32 v[96:97], v[82:83], v[80:81]
	v_add_f32_e32 v81, v84, v171
	v_pk_add_f32 v[96:97], v[96:97], v[96:97] op_sel_hi:[0,1]
	v_add_f32_e32 v83, v100, v171
	v_add_f32_e32 v84, v85, v171
	v_exp_f32_e32 v81, v81
	v_exp_f32_e32 v83, v83
	v_exp_f32_e32 v96, v84
	v_add_f32_e32 v84, v101, v171
	v_exp_f32_e32 v84, v84
	v_add_f32_e32 v85, v83, v81
	v_cvt_pk_bf16_f32 v150, v81, v96
	v_cvt_pk_bf16_f32 v153, v153, v82
	v_pk_add_f32 v[98:99], v[84:85], v[96:97]
	v_add_f32_e32 v85, v86, v171
	v_add_f32_e32 v86, v102, v171
	v_pk_add_f32 v[98:99], v[98:99], v[98:99] op_sel_hi:[0,1]
	v_exp_f32_e32 v97, v86
	v_add_f32_e32 v86, v87, v171
	v_exp_f32_e32 v85, v85
	v_exp_f32_e32 v98, v86
	v_add_f32_e32 v86, v103, v171
	v_exp_f32_e32 v86, v86
	v_add_f32_e32 v87, v97, v85
	v_cvt_pk_bf16_f32 v151, v85, v98
	v_cvt_pk_bf16_f32 v154, v83, v84
	v_pk_add_f32 v[100:101], v[86:87], v[98:99]
	v_add_f32_e32 v87, v88, v171
	v_add_f32_e32 v88, v104, v171
	v_pk_add_f32 v[100:101], v[100:101], v[100:101] op_sel_hi:[0,1]
	v_exp_f32_e32 v99, v88
	v_add_f32_e32 v88, v89, v171
	v_exp_f32_e32 v87, v87
	v_exp_f32_e32 v100, v88
	v_add_f32_e32 v88, v105, v171
	v_exp_f32_e32 v88, v88
	v_add_f32_e32 v89, v99, v87
	v_cvt_pk_bf16_f32 v155, v97, v86
	v_cvt_pk_bf16_f32 v156, v87, v100
	v_pk_add_f32 v[102:103], v[88:89], v[100:101]
	v_add_f32_e32 v89, v90, v171
	v_add_f32_e32 v90, v106, v171
	v_pk_add_f32 v[102:103], v[102:103], v[102:103] op_sel_hi:[0,1]
	v_exp_f32_e32 v101, v90
	v_add_f32_e32 v90, v91, v171
	v_exp_f32_e32 v89, v89
	v_exp_f32_e32 v102, v90
	v_add_f32_e32 v90, v107, v171
	v_exp_f32_e32 v90, v90
	v_add_f32_e32 v91, v101, v89
	v_cvt_pk_bf16_f32 v157, v89, v102
	v_cvt_pk_bf16_f32 v160, v99, v88
	v_pk_add_f32 v[104:105], v[90:91], v[102:103]
	v_add_f32_e32 v91, v92, v171
	v_add_f32_e32 v92, v108, v171
	v_pk_add_f32 v[104:105], v[104:105], v[104:105] op_sel_hi:[0,1]
	v_exp_f32_e32 v103, v92
	v_add_f32_e32 v92, v93, v171
	v_exp_f32_e32 v91, v91
	v_exp_f32_e32 v104, v92
	v_add_f32_e32 v92, v109, v171
	v_exp_f32_e32 v92, v92
	v_add_f32_e32 v93, v103, v91
	v_cvt_pk_bf16_f32 v158, v91, v104
	v_cvt_pk_bf16_f32 v161, v101, v90
	v_pk_add_f32 v[106:107], v[92:93], v[104:105]
	v_add_f32_e32 v93, v94, v171
	v_add_f32_e32 v94, v110, v171
	v_pk_add_f32 v[106:107], v[106:107], v[106:107] op_sel_hi:[0,1]
	v_exp_f32_e32 v105, v94
	v_add_f32_e32 v94, v95, v171
	v_exp_f32_e32 v93, v93
	v_exp_f32_e32 v106, v94
	v_add_f32_e32 v94, v111, v171
	v_exp_f32_e32 v94, v94
	v_add_f32_e32 v95, v105, v93
	v_cvt_pk_bf16_f32 v159, v93, v106
	v_cvt_pk_bf16_f32 v162, v103, v92
	v_pk_add_f32 v[108:109], v[94:95], v[106:107]
	v_cvt_pk_bf16_f32 v163, v105, v94
	v_add_f32_e32 v95, v108, v109
	v_add_f32_e32 v175, v175, v95

.LBB0_464:
	s_waitcnt vmcnt(5)
	v_and_b32_e32 v0, 0xffff, v2
	v_lshrrev_b32_e32 v2, 16, v2
	s_waitcnt vmcnt(4)
	v_lshl_or_b32 v0, v6, 16, v0
	v_and_or_b32 v2, v6, s57, v2
	ds_write2_b32 v178, v0, v2 offset1:34
	v_and_b32_e32 v0, 0xffff, v3
	v_lshrrev_b32_e32 v2, 16, v3
	v_lshl_or_b32 v0, v7, 16, v0
	v_and_or_b32 v2, v7, s57, v2
	ds_write2_b32 v178, v0, v2 offset0:68 offset1:102
	v_and_b32_e32 v0, 0xffff, v4
	v_lshrrev_b32_e32 v2, 16, v4
	v_lshl_or_b32 v0, v8, 16, v0
	v_and_or_b32 v2, v8, s57, v2
	s_add_i32 s44, s44, 2
	ds_write2_b32 v178, v0, v2 offset0:136 offset1:170
	v_and_b32_e32 v0, 0xffff, v5
	v_lshrrev_b32_e32 v2, 16, v5
	s_addk_i32 s45, 0x80
	v_lshl_or_b32 v0, v9, 16, v0
	v_and_or_b32 v2, v9, s57, v2
	s_cmp_gt_i32 s44, s41
	ds_write2_b32 v178, v0, v2 offset0:204 offset1:238
	s_waitcnt lgkmcnt(0)
	s_barrier
	s_cselect_b64 s[20:21], -1, 0
	s_and_b64 vcc, exec, s[20:21]
	s_cbranch_vccz .LBB0_451
	s_branch .LBB0_465

.Lqf_454:
	s_nop 8
	v_exp_f32_e32 v132, v80
	v_exp_f32_e32 v136, v96
	v_exp_f32_e32 v0, v81
	v_exp_f32_e32 v80, v97
	v_add_f32_e32 v81, v136, v132
	v_cvt_pk_bf16_f32 v132, v132, v0
	v_pk_add_f32 v[96:97], v[80:81], v[0:1]
	v_pk_add_f32 v[96:97], v[96:97], v[96:97] op_sel_hi:[0,1]
	v_exp_f32_e32 v137, v98
	v_exp_f32_e32 v81, v82
	v_exp_f32_e32 v96, v83
	v_exp_f32_e32 v82, v99
	v_add_f32_e32 v83, v137, v81
	v_cvt_pk_bf16_f32 v133, v81, v96
	v_cvt_pk_bf16_f32 v136, v136, v80
	v_pk_add_f32 v[98:99], v[82:83], v[96:97]
	v_pk_add_f32 v[98:99], v[98:99], v[98:99] op_sel_hi:[0,1]
	v_exp_f32_e32 v97, v100
	v_exp_f32_e32 v83, v84
	v_exp_f32_e32 v98, v85
	v_exp_f32_e32 v84, v101
	v_add_f32_e32 v85, v97, v83
	v_cvt_pk_bf16_f32 v134, v83, v98
	v_cvt_pk_bf16_f32 v137, v137, v82
	v_pk_add_f32 v[100:101], v[84:85], v[98:99]
	v_pk_add_f32 v[100:101], v[100:101], v[100:101] op_sel_hi:[0,1]
	v_exp_f32_e32 v99, v102
	v_exp_f32_e32 v85, v86
	v_exp_f32_e32 v100, v87
	v_exp_f32_e32 v86, v103
	v_add_f32_e32 v87, v99, v85
	v_cvt_pk_bf16_f32 v135, v85, v100
	v_cvt_pk_bf16_f32 v138, v97, v84
	v_pk_add_f32 v[102:103], v[86:87], v[100:101]
	v_pk_add_f32 v[102:103], v[102:103], v[102:103] op_sel_hi:[0,1]
	v_exp_f32_e32 v101, v104
	v_exp_f32_e32 v87, v88
	v_exp_f32_e32 v102, v89
	v_exp_f32_e32 v88, v105
	v_add_f32_e32 v89, v101, v87
	v_cvt_pk_bf16_f32 v139, v99, v86
	v_cvt_pk_bf16_f32 v140, v87, v102
	v_pk_add_f32 v[104:105], v[88:89], v[102:103]
	v_pk_add_f32 v[104:105], v[104:105], v[104:105] op_sel_hi:[0,1]
	v_exp_f32_e32 v103, v106
	v_exp_f32_e32 v89, v90
	v_exp_f32_e32 v104, v91
	v_exp_f32_e32 v90, v107
	v_add_f32_e32 v91, v103, v89
	v_cvt_pk_bf16_f32 v141, v89, v104
	v_cvt_pk_bf16_f32 v144, v101, v88
	v_pk_add_f32 v[106:107], v[90:91], v[104:105]
	v_pk_add_f32 v[106:107], v[106:107], v[106:107] op_sel_hi:[0,1]
	v_exp_f32_e32 v105, v108
	v_exp_f32_e32 v91, v92
	v_exp_f32_e32 v106, v93
	v_exp_f32_e32 v92, v109
	v_add_f32_e32 v93, v105, v91
	v_cvt_pk_bf16_f32 v142, v91, v106
	v_cvt_pk_bf16_f32 v145, v103, v90
	v_pk_add_f32 v[108:109], v[92:93], v[106:107]
	v_pk_add_f32 v[108:109], v[108:109], v[108:109] op_sel_hi:[0,1]
	v_exp_f32_e32 v107, v110
	v_exp_f32_e32 v93, v94
	v_exp_f32_e32 v108, v95
	v_exp_f32_e32 v94, v111
	v_add_f32_e32 v95, v107, v93
	v_cvt_pk_bf16_f32 v143, v93, v108
	v_cvt_pk_bf16_f32 v146, v105, v92
	v_pk_add_f32 v[110:111], v[94:95], v[108:109]
	v_cvt_pk_bf16_f32 v147, v107, v94
	v_add_f32_e32 v95, v110, v111
	v_add_f32_e32 v175, v175, v95

.Lqf_461:
	s_nop 8
	v_exp_f32_e32 v148, v80
	v_exp_f32_e32 v152, v96
	v_exp_f32_e32 v0, v81
	v_exp_f32_e32 v14, v97
	v_add_f32_e32 v15, v152, v148
	v_cvt_pk_bf16_f32 v148, v148, v0
	v_pk_add_f32 v[80:81], v[14:15], v[0:1]
	v_pk_add_f32 v[80:81], v[80:81], v[80:81] op_sel_hi:[0,1]
	v_exp_f32_e32 v15, v82
	v_exp_f32_e32 v153, v98
	v_exp_f32_e32 v80, v83
	v_exp_f32_e32 v82, v99
	v_add_f32_e32 v83, v153, v15
	v_cvt_pk_bf16_f32 v152, v152, v14
	v_cvt_pk_bf16_f32 v149, v15, v80
	v_pk_add_f32 v[96:97], v[82:83], v[80:81]
	v_pk_add_f32 v[96:97], v[96:97], v[96:97] op_sel_hi:[0,1]
	v_exp_f32_e32 v81, v84
	v_exp_f32_e32 v83, v100
	v_exp_f32_e32 v96, v85
	v_exp_f32_e32 v84, v101
	v_add_f32_e32 v85, v83, v81
	v_cvt_pk_bf16_f32 v150, v81, v96
	v_cvt_pk_bf16_f32 v153, v153, v82
	v_pk_add_f32 v[98:99], v[84:85], v[96:97]
	v_pk_add_f32 v[98:99], v[98:99], v[98:99] op_sel_hi:[0,1]
	v_exp_f32_e32 v97, v102
	v_exp_f32_e32 v85, v86
	v_exp_f32_e32 v98, v87
	v_exp_f32_e32 v86, v103
	v_add_f32_e32 v87, v97, v85
	v_cvt_pk_bf16_f32 v151, v85, v98
	v_cvt_pk_bf16_f32 v154, v83, v84
	v_pk_add_f32 v[100:101], v[86:87], v[98:99]
	v_pk_add_f32 v[100:101], v[100:101], v[100:101] op_sel_hi:[0,1]
	v_exp_f32_e32 v99, v104
	v_exp_f32_e32 v87, v88
	v_exp_f32_e32 v100, v89
	v_exp_f32_e32 v88, v105
	v_add_f32_e32 v89, v99, v87
	v_cvt_pk_bf16_f32 v155, v97, v86
	v_cvt_pk_bf16_f32 v156, v87, v100
	v_pk_add_f32 v[102:103], v[88:89], v[100:101]
	v_pk_add_f32 v[102:103], v[102:103], v[102:103] op_sel_hi:[0,1]
	v_exp_f32_e32 v101, v106
	v_exp_f32_e32 v89, v90
	v_exp_f32_e32 v102, v91
	v_exp_f32_e32 v90, v107
	v_add_f32_e32 v91, v101, v89
	v_cvt_pk_bf16_f32 v157, v89, v102
	v_cvt_pk_bf16_f32 v160, v99, v88
	v_pk_add_f32 v[104:105], v[90:91], v[102:103]
	v_pk_add_f32 v[104:105], v[104:105], v[104:105] op_sel_hi:[0,1]
	v_exp_f32_e32 v103, v108
	v_exp_f32_e32 v91, v92
	v_exp_f32_e32 v104, v93
	v_exp_f32_e32 v92, v109
	v_add_f32_e32 v93, v103, v91
	v_cvt_pk_bf16_f32 v158, v91, v104
	v_cvt_pk_bf16_f32 v161, v101, v90
	v_pk_add_f32 v[106:107], v[92:93], v[104:105]
	v_pk_add_f32 v[106:107], v[106:107], v[106:107] op_sel_hi:[0,1]
	v_exp_f32_e32 v105, v110
	v_exp_f32_e32 v93, v94
	v_exp_f32_e32 v106, v95
	v_exp_f32_e32 v94, v111
	v_add_f32_e32 v95, v105, v93
	v_cvt_pk_bf16_f32 v159, v93, v106
	v_cvt_pk_bf16_f32 v162, v103, v92
	v_pk_add_f32 v[108:109], v[94:95], v[106:107]
	v_cvt_pk_bf16_f32 v163, v105, v94
	v_add_f32_e32 v95, v108, v109
	v_add_f32_e32 v175, v175, v95
